# phase 1 stagger: half of the non-context workgroups stream norm_rows first and do their filter item afterwards
# speedup vs baseline: 1.0018x; 1.0018x over previous
.LBB0_214:
	s_cmp_lt_i32 s92, 2
	s_cselect_b64 s[4:5], -1, 0
	s_and_b64 s[0:1], s[4:5], s[0:1]
	s_andn2_b64 vcc, exec, s[0:1]
	s_cbranch_vccnz .LBB0_299
	s_mov_b32 s100, 0
	s_cmp_gt_u32 s34, 63
	s_cselect_b64 s[0:1], -1, 0
	s_cmp_lt_u32 s34, 64
	s_cselect_b64 s[8:9], -1, 0
	s_and_b64 vcc, exec, s[8:9]
	s_cbranch_vccnz .LBB0_218
	s_cmp_gt_u32 s20, 31
	s_cbranch_scc0 .LBB0_219
	s_sub_i32 s24, s20, 32
	s_mov_b64 s[6:7], 0
	s_cbranch_execnz .LBB0_220
	s_branch .LBB0_281

.LBB0_220:
	s_sub_i32 s2, s34, 32
	s_and_b64 s[0:1], s[0:1], exec
	s_cselect_b32 s25, s2, s34
	s_cmpk_gt_i32 s24, 0xff
	s_cbranch_scc1 .LBB0_227
	s_cmp_lg_u32 s34, 0x100
	s_cbranch_scc1 .Lp1_filt4_entry
	s_bitcmp0_b32 s20, 3
	s_cbranch_scc1 .Lp1_filt4_entry
	s_mov_b32 s100, 1
	s_branch .LBB0_227
.Lp1_filt4_entry:
	v_cvt_f32_u32_e32 v0, v160
	s_lshl_b32 s26, s24, 4
	s_lshl_b32 s27, s25, 4
	s_add_u32 s28, s22, 0x1cb6000
	s_addc_u32 s29, s23, 0
	v_mov_b32_e32 v161, 0xc0447cbd
	v_lshlrev_b32_e32 v38, 2, v160
	v_mov_b32_e32 v39, 0
	v_readlane_b32 s36, v240, 24
	s_bitcmp1_b32 s24, 0
	v_fmac_f32_e32 v161, 0xbcc4df2d, v0
	v_lshl_add_u64 v[0:1], s[22:23], 0, v[38:39]
	s_mov_b64 s[0:1], 0x2cb6000
	v_readlane_b32 s38, v240, 26
	v_readlane_b32 s39, v240, 27
	v_readlane_b32 s42, v240, 30
	v_readlane_b32 s43, v240, 31
	v_readlane_b32 s44, v240, 32
	v_readlane_b32 s45, v240, 33
	v_readlane_b32 s46, v240, 34
	v_readlane_b32 s47, v240, 35
	s_mov_b64 s[2:3], 0x1bb6000
	s_cselect_b64 s[10:11], -1, 0
	s_bitcmp1_b32 s25, 0
	v_lshlrev_b32_e32 v184, 12, v160
	v_lshl_add_u64 v[40:41], v[0:1], 0, s[0:1]
	v_lshl_add_u64 v[42:43], s[42:43], 0, v[38:39]
	v_add_u32_e32 v185, 0xfffffe00, v160
	s_mov_b32 s1, 0
	v_add_u32_e32 v186, 0, v38
	v_lshl_add_u64 v[44:45], v[0:1], 0, s[2:3]
	s_cselect_b64 s[12:13], -1, 0
	s_mov_b32 s30, 0xe000
	s_mov_b32 s31, 0x10000
	s_mov_b32 s38, 0x12000
	s_mov_b32 s39, 0x14000
	s_mov_b32 s42, 0x16000
	s_mov_b32 s43, 0x18000
	s_mov_b32 s44, 0x1a000
	s_mov_b32 s45, 0x1c000
	s_mov_b32 s46, 0x1e000
	s_mov_b32 s47, 0x20000
	s_mov_b32 s62, 0x22000
	s_mov_b32 s63, 0x24000
	s_mov_b32 s64, 0x26000
	s_mov_b32 s65, 0x28000
	s_mov_b32 s66, 0x2a000
	s_mov_b32 s67, 0x2c000
	s_mov_b32 s68, 0x2e000
	s_mov_b32 s69, 0x30000
	s_mov_b32 s70, 0x32000
	s_mov_b32 s71, 0x34000
	s_mov_b32 s72, 0x36000
	s_mov_b32 s73, 0x38000
	s_mov_b32 s74, 0x3a000
	s_mov_b32 s75, 0x3c000
	s_mov_b32 s76, 0x3e000
	s_mov_b32 s77, 0x3f000
	s_mov_b32 s78, 0xc57ff000
	s_mov_b32 s79, s24
	v_readlane_b32 s37, v240, 25
	v_readlane_b32 s40, v240, 28
	v_readlane_b32 s41, v240, 29
	v_readlane_b32 s48, v240, 36
	v_readlane_b32 s49, v240, 37
	v_readlane_b32 s50, v240, 38
	v_readlane_b32 s51, v240, 39

.LBB0_227:
	s_cmp_eq_u32 s100, 2
	s_cbranch_scc1 .LBB0_281
	s_add_u32 s2, s22, 0x30bc000
	s_addc_u32 s3, s23, 0
	s_lshl_b32 s29, s25, 3
	s_abs_i32 s28, s29
	v_cvt_f32_u32_e32 v0, s28
	s_add_i32 s0, s29, 0x7fff
	s_sub_i32 s10, 0xffff8001, s29
	s_ashr_i32 s1, s0, 31
	v_rcp_iflag_f32_e32 v0, v0
	s_max_i32 s0, s0, s10
	s_sub_i32 s10, 0, s28
	s_ashr_i32 s30, s29, 31
	v_mul_f32_e32 v0, 0x4f7ffffe, v0
	v_cvt_u32_f32_e32 v0, v0
	s_xor_b32 s1, s1, s30
	v_lshrrev_b32_e32 v1, 6, v160
	v_lshl_add_u32 v99, s24, 3, v1
	v_readfirstlane_b32 s31, v0
	s_mul_i32 s10, s10, s31
	s_mul_hi_u32 s10, s31, s10
	s_add_i32 s31, s31, s10
	s_mul_hi_u32 s10, s0, s31
	s_mul_i32 s11, s10, s28
	s_sub_i32 s0, s0, s11
	s_add_i32 s11, s10, 1
	s_sub_i32 s12, s0, s28
	s_cmp_ge_u32 s0, s28
	s_cselect_b32 s10, s11, s10
	s_cselect_b32 s0, s12, s0
	s_add_i32 s11, s10, 1
	s_cmp_ge_u32 s0, s28
	s_cselect_b32 s0, s11, s10
	s_xor_b32 s0, s0, s1
	s_sub_i32 s0, s0, s1
	v_mul_lo_u32 v48, s0, v99
	v_add_u32_e32 v0, s0, v48
	v_min_i32_e32 v103, 0x8000, v0
	v_cmp_lt_i32_e32 vcc, v48, v103
	s_and_saveexec_b64 s[10:11], vcc
	s_cbranch_execz .LBB0_256
	v_ashrrev_i32_e32 v49, 31, v48
	v_readlane_b32 s36, v240, 8
	v_lshlrev_b32_e32 v2, 2, v160
	v_lshlrev_b64 v[0:1], 12, v[48:49]
	v_readlane_b32 s37, v240, 9
	v_and_b32_e32 v52, 0xfc, v2
	v_mov_b32_e32 v97, 0
	v_lshl_add_u64 v[0:1], s[36:37], 0, v[0:1]
	v_lshlrev_b32_e32 v96, 2, v52
	v_lshl_add_u64 v[12:13], v[0:1], 0, v[96:97]
	global_load_dwordx4 v[0:3], v[12:13], off nt
	global_load_dwordx4 v[4:7], v[12:13], off offset:1024 nt
	global_load_dwordx4 v[8:11], v[12:13], off offset:2048 nt
	s_nop 0
	global_load_dwordx4 v[12:15], v[12:13], off offset:3072 nt
	v_add_u32_e32 v32, 1, v48
	v_cmp_lt_i32_e32 vcc, v32, v103
	v_readlane_b32 s38, v240, 10
	v_readlane_b32 s39, v240, 11
	v_readlane_b32 s40, v240, 12
	v_readlane_b32 s41, v240, 13
	v_readlane_b32 s42, v240, 14
	v_readlane_b32 s43, v240, 15
	v_readlane_b32 s44, v240, 16
	v_readlane_b32 s45, v240, 17
	v_readlane_b32 s46, v240, 18
	v_readlane_b32 s47, v240, 19
	v_readlane_b32 s48, v240, 20
	v_readlane_b32 s49, v240, 21
	v_readlane_b32 s50, v240, 22
	v_readlane_b32 s51, v240, 23
	s_and_saveexec_b64 s[0:1], vcc
	s_cbranch_execz .LBB0_230
	v_ashrrev_i32_e32 v33, 31, v32
	v_readlane_b32 s36, v240, 8
	s_waitcnt vmcnt(12)
	v_lshlrev_b64 v[16:17], 12, v[32:33]
	v_readlane_b32 s37, v240, 9
	v_readlane_b32 s38, v240, 10
	v_readlane_b32 s39, v240, 11
	v_lshl_add_u64 v[16:17], s[36:37], 0, v[16:17]
	v_lshl_add_u64 v[28:29], v[16:17], 0, v[96:97]
	global_load_dwordx4 v[16:19], v[28:29], off nt
	global_load_dwordx4 v[20:23], v[28:29], off offset:1024 nt
	global_load_dwordx4 v[24:27], v[28:29], off offset:2048 nt
	s_nop 0
	global_load_dwordx4 v[28:31], v[28:29], off offset:3072 nt
	v_readlane_b32 s40, v240, 12
	v_readlane_b32 s41, v240, 13
	v_readlane_b32 s42, v240, 14
	v_readlane_b32 s43, v240, 15
	v_readlane_b32 s44, v240, 16
	v_readlane_b32 s45, v240, 17
	v_readlane_b32 s46, v240, 18
	v_readlane_b32 s47, v240, 19
	v_readlane_b32 s48, v240, 20
	v_readlane_b32 s49, v240, 21
	v_readlane_b32 s50, v240, 22
	v_readlane_b32 s51, v240, 23

.LBB0_281:
	s_cmp_lg_u32 s100, 1
	s_cbranch_scc1 .Lp1_join
	s_mov_b32 s100, 2
	s_sub_i32 s24, s20, 32
	s_sub_i32 s25, s34, 32
	s_branch .Lp1_filt4_entry
